# E1 pooling loop: each wave cycles through the four window groups across its iterations (balanced per-wave work)
# speedup vs baseline: 1.0062x; 1.0001x over previous
.LBB0_238:
	v_ashrrev_i32_e32 v17, 6, v51
	v_lshrrev_b32_e32 v0, 4, v51
	v_bfi_b32 v16, -4, v17, v0
	v_lshlrev_b32_e32 v0, 3, v51
	v_cmp_gt_i32_e32 vcc, s7, v16
	v_bfe_u32 v53, v51, 6, 2
	v_lshrrev_b32_e32 v255, 17, v51
	v_add_u32_e32 v53, v53, v255
	v_and_b32_e32 v53, 3, v53
	s_waitcnt vmcnt(1)
	v_and_b32_e32 v4, -4, v17
	v_and_b32_e32 v0, 0x78, v0
	v_bfe_u32 v5, v51, 4, 2
	v_cndmask_b32_e32 v6, 7, v35, vcc
	v_lshl_or_b32 v52, v53, 7, v0
	v_bitop3_b32 v54, v6, v4, v5 bitop3:0xe0
	v_mad_i64_i32 v[0:1], s[8:9], v16, s33, v[12:13]
	v_lshlrev_b32_e32 v14, 1, v52
	v_cmp_eq_u32_e64 s[10:11], 0, v54
	v_lshl_add_u64 v[26:27], v[0:1], 0, v[14:15]
	global_load_dwordx4 v[0:3], v[26:27], off offset:3584
	v_cndmask_b32_e64 v5, -1, 0, s[10:11]
	v_cndmask_b32_e64 v4, v36, 0, s[10:11]
	v_lshl_add_u64 v[4:5], v[26:27], 0, v[4:5]
	global_load_dwordx4 v[8:11], v[4:5], off offset:3584
	v_cmp_lt_i32_e64 s[8:9], s6, v16
	v_cmp_lt_i32_e64 s[12:13], 1, v53
	s_waitcnt vmcnt(1)
	v_lshlrev_b32_e32 v20, 16, v0
	v_and_b32_e32 v21, 0xffff0000, v0
	v_lshlrev_b32_e32 v24, 16, v1
	v_and_b32_e32 v25, 0xffff0000, v1
	v_lshlrev_b32_e32 v18, 16, v2
	v_and_b32_e32 v19, 0xffff0000, v2
	v_lshlrev_b32_e32 v22, 16, v3
	v_and_b32_e32 v23, 0xffff0000, v3
	s_and_saveexec_b64 s[14:15], s[12:13]
	s_xor_b64 s[70:71], exec, s[14:15]
	s_cbranch_execz .LBB0_244
	v_cmp_lt_i32_e64 s[12:13], 2, v53
	s_and_saveexec_b64 s[14:15], s[12:13]
	s_xor_b64 s[72:73], exec, s[14:15]
	s_cbranch_execz .LBB0_241
	v_cmp_gt_u32_e64 s[40:41], 2, v54
	v_cmp_gt_u32_e64 s[36:37], 4, v54
	v_cmp_gt_u32_e64 s[38:39], 3, v54
	v_cndmask_b32_e64 v1, -1, 0, s[40:41]
	v_cndmask_b32_e64 v0, v37, 0, s[40:41]
	v_cndmask_b32_e64 v3, -1, 0, s[36:37]
	v_cndmask_b32_e64 v2, v39, 0, s[36:37]
	v_lshl_add_u64 v[0:1], v[26:27], 0, v[0:1]
	v_lshl_add_u64 v[2:3], v[26:27], 0, v[2:3]
	global_load_dwordx4 v[28:31], v[0:1], off offset:3584
	global_load_dwordx4 v[60:63], v[2:3], off offset:3584
	v_cndmask_b32_e64 v1, -1, 0, s[38:39]
	v_cndmask_b32_e64 v0, v38, 0, s[38:39]
	v_cmp_gt_u32_e64 s[34:35], 5, v54
	v_lshl_add_u64 v[0:1], v[26:27], 0, v[0:1]
	v_cmp_gt_u32_e64 s[30:31], 6, v54
	v_cndmask_b32_e64 v5, -1, 0, s[34:35]
	global_load_dwordx4 v[56:59], v[0:1], off offset:3584
	v_cndmask_b32_e64 v4, v40, 0, s[34:35]
	v_cndmask_b32_e64 v7, -1, 0, s[30:31]
	v_cmp_gt_u32_e64 s[28:29], 7, v54
	v_lshl_add_u64 v[4:5], v[26:27], 0, v[4:5]
	v_cndmask_b32_e64 v6, v41, 0, s[30:31]
	v_cmp_gt_u32_e64 s[24:25], 9, v54
	global_load_dwordx4 v[64:67], v[4:5], off offset:3584
	v_cndmask_b32_e64 v1, -1, 0, s[28:29]
	v_cndmask_b32_e64 v0, v42, 0, s[28:29]
	v_lshl_add_u64 v[6:7], v[26:27], 0, v[6:7]
	v_cndmask_b32_e64 v69, -1, 0, s[24:25]
	s_waitcnt vmcnt(4)
	v_lshlrev_b32_e32 v70, 16, v8
	v_and_b32_e32 v71, 0xffff0000, v8
	v_lshlrev_b32_e32 v82, 16, v9
	v_and_b32_e32 v83, 0xffff0000, v9
	v_lshlrev_b32_e32 v4, 16, v10
	v_and_b32_e32 v5, 0xffff0000, v10
	v_lshlrev_b32_e32 v84, 16, v11
	v_and_b32_e32 v85, 0xffff0000, v11
	v_cndmask_b32_e64 v86, 1.0, 0, s[10:11]
	v_cndmask_b32_e64 v68, v44, 0, s[24:25]
	global_load_dwordx4 v[8:11], v[6:7], off offset:3584
	v_lshl_add_u64 v[0:1], v[26:27], 0, v[0:1]
	v_pk_fma_f32 v[98:99], v[86:87], v[70:71], v[20:21] op_sel_hi:[0,1,1]
	v_lshl_add_u64 v[6:7], v[26:27], 0, v[68:69]
	global_load_dwordx4 v[68:71], v[0:1], off offset:3584
	v_cmp_gt_u32_e64 s[26:27], 8, v54
	v_cmp_gt_u32_e64 s[22:23], 10, v54
	v_cmp_gt_u32_e64 s[18:19], 12, v54
	v_cmp_gt_u32_e64 s[16:17], 13, v54
	v_cndmask_b32_e64 v33, -1, 0, s[26:27]
	v_cndmask_b32_e64 v73, -1, 0, s[22:23]
	v_cmp_gt_u32_e64 s[20:21], 11, v54
	v_cndmask_b32_e64 v3, -1, 0, s[18:19]
	v_cndmask_b32_e64 v77, -1, 0, s[16:17]
	v_cmp_gt_u32_e64 s[14:15], 14, v54
	v_cmp_gt_u32_e64 s[12:13], 15, v54
	v_cndmask_b32_e64 v32, v43, 0, s[26:27]
	v_cndmask_b32_e64 v72, v45, 0, s[22:23]
	v_cndmask_b32_e64 v2, v47, 0, s[18:19]
	v_cndmask_b32_e64 v76, v48, 0, s[16:17]
	v_cndmask_b32_e64 v75, -1, 0, s[20:21]
	v_cndmask_b32_e64 v79, -1, 0, s[14:15]
	v_cndmask_b32_e64 v81, -1, 0, s[12:13]
	v_cndmask_b32_e64 v74, v46, 0, s[20:21]
	v_cndmask_b32_e64 v78, v49, 0, s[14:15]
	v_cndmask_b32_e64 v80, v50, 0, s[12:13]
	v_pk_fma_f32 v[102:103], v[86:87], v[4:5], v[18:19] op_sel_hi:[0,1,1]
	v_lshl_add_u64 v[4:5], v[26:27], 0, v[32:33]
	v_lshl_add_u64 v[0:1], v[26:27], 0, v[72:73]
	v_lshl_add_u64 v[2:3], v[26:27], 0, v[2:3]
	v_lshl_add_u64 v[92:93], v[26:27], 0, v[76:77]
	v_pk_fma_f32 v[96:97], v[86:87], v[82:83], v[24:25] op_sel_hi:[0,1,1]
	v_pk_fma_f32 v[100:101], v[86:87], v[84:85], v[22:23] op_sel_hi:[0,1,1]
	v_lshl_add_u64 v[32:33], v[26:27], 0, v[74:75]
	v_lshl_add_u64 v[104:105], v[26:27], 0, v[78:79]
	v_lshl_add_u64 v[26:27], v[26:27], 0, v[80:81]
	global_load_dwordx4 v[72:75], v[4:5], off offset:3584
	global_load_dwordx4 v[76:79], v[6:7], off offset:3584
	global_load_dwordx4 v[80:83], v[0:1], off offset:3584
	global_load_dwordx4 v[84:87], v[32:33], off offset:3584
	global_load_dwordx4 v[88:91], v[2:3], off offset:3584
	s_nop 0
	global_load_dwordx4 v[92:95], v[92:93], off offset:3584
	s_nop 0
	global_load_dwordx4 v[4:7], v[104:105], off offset:3584
	global_load_dwordx4 v[0:3], v[26:27], off offset:3584
	v_cndmask_b32_e64 v104, 1.0, 0, s[40:41]
	s_waitcnt vmcnt(13)
	v_lshlrev_b32_e32 v26, 16, v28
	v_and_b32_e32 v27, 0xffff0000, v28
	v_lshlrev_b32_e32 v28, 16, v29
	v_and_b32_e32 v29, 0xffff0000, v29
	v_lshlrev_b32_e32 v32, 16, v30
	v_and_b32_e32 v33, 0xffff0000, v30
	v_lshlrev_b32_e32 v30, 16, v31
	v_and_b32_e32 v31, 0xffff0000, v31
	v_pk_fma_f32 v[26:27], v[104:105], v[26:27], v[98:99] op_sel_hi:[0,1,1]
	v_pk_fma_f32 v[28:29], v[104:105], v[28:29], v[96:97] op_sel_hi:[0,1,1]
	v_pk_fma_f32 v[32:33], v[104:105], v[32:33], v[102:103] op_sel_hi:[0,1,1]
	v_pk_fma_f32 v[30:31], v[104:105], v[30:31], v[100:101] op_sel_hi:[0,1,1]
	s_waitcnt vmcnt(11)
	v_lshlrev_b32_e32 v96, 16, v56
	v_and_b32_e32 v97, 0xffff0000, v56
	v_lshlrev_b32_e32 v56, 16, v57
	v_and_b32_e32 v57, 0xffff0000, v57
	v_lshlrev_b32_e32 v98, 16, v58
	v_and_b32_e32 v99, 0xffff0000, v58
	v_lshlrev_b32_e32 v58, 16, v59
	v_and_b32_e32 v59, 0xffff0000, v59
	v_cndmask_b32_e64 v100, 1.0, 0, s[38:39]
	v_pk_fma_f32 v[28:29], v[100:101], v[56:57], v[28:29] op_sel_hi:[0,1,1]
	v_pk_fma_f32 v[26:27], v[100:101], v[96:97], v[26:27] op_sel_hi:[0,1,1]
	v_pk_fma_f32 v[30:31], v[100:101], v[58:59], v[30:31] op_sel_hi:[0,1,1]
	v_pk_fma_f32 v[32:33], v[100:101], v[98:99], v[32:33] op_sel_hi:[0,1,1]
	v_lshlrev_b32_e32 v56, 16, v60
	v_and_b32_e32 v57, 0xffff0000, v60
	v_lshlrev_b32_e32 v58, 16, v61
	v_and_b32_e32 v59, 0xffff0000, v61
	v_lshlrev_b32_e32 v60, 16, v62
	v_and_b32_e32 v61, 0xffff0000, v62
	v_lshlrev_b32_e32 v62, 16, v63
	v_and_b32_e32 v63, 0xffff0000, v63
	v_cndmask_b32_e64 v96, 1.0, 0, s[36:37]
	v_pk_fma_f32 v[26:27], v[96:97], v[56:57], v[26:27] op_sel_hi:[0,1,1]
	v_pk_fma_f32 v[28:29], v[96:97], v[58:59], v[28:29] op_sel_hi:[0,1,1]
	v_pk_fma_f32 v[32:33], v[96:97], v[60:61], v[32:33] op_sel_hi:[0,1,1]
	v_pk_fma_f32 v[30:31], v[96:97], v[62:63], v[30:31] op_sel_hi:[0,1,1]
	s_waitcnt vmcnt(10)
	v_lshlrev_b32_e32 v56, 16, v64
	v_and_b32_e32 v57, 0xffff0000, v64
	v_lshlrev_b32_e32 v58, 16, v65
	v_and_b32_e32 v59, 0xffff0000, v65
	v_lshlrev_b32_e32 v60, 16, v66
	v_and_b32_e32 v61, 0xffff0000, v66
	v_lshlrev_b32_e32 v62, 16, v67
	v_and_b32_e32 v63, 0xffff0000, v67
	v_cndmask_b32_e64 v64, 1.0, 0, s[34:35]
	v_pk_fma_f32 v[28:29], v[64:65], v[58:59], v[28:29] op_sel_hi:[0,1,1]
	v_pk_fma_f32 v[26:27], v[64:65], v[56:57], v[26:27] op_sel_hi:[0,1,1]
	v_pk_fma_f32 v[30:31], v[64:65], v[62:63], v[30:31] op_sel_hi:[0,1,1]
	v_pk_fma_f32 v[32:33], v[64:65], v[60:61], v[32:33] op_sel_hi:[0,1,1]
	s_waitcnt vmcnt(9)
	v_lshlrev_b32_e32 v56, 16, v8
	v_and_b32_e32 v57, 0xffff0000, v8
	v_lshlrev_b32_e32 v8, 16, v9
	v_and_b32_e32 v9, 0xffff0000, v9
	v_lshlrev_b32_e32 v58, 16, v10
	v_and_b32_e32 v59, 0xffff0000, v10
	v_lshlrev_b32_e32 v10, 16, v11
	v_and_b32_e32 v11, 0xffff0000, v11
	v_cndmask_b32_e64 v60, 1.0, 0, s[30:31]
	v_pk_fma_f32 v[26:27], v[60:61], v[56:57], v[26:27] op_sel_hi:[0,1,1]
	v_pk_fma_f32 v[8:9], v[60:61], v[8:9], v[28:29] op_sel_hi:[0,1,1]
	v_pk_fma_f32 v[28:29], v[60:61], v[58:59], v[32:33] op_sel_hi:[0,1,1]
	v_pk_fma_f32 v[10:11], v[60:61], v[10:11], v[30:31] op_sel_hi:[0,1,1]
	s_waitcnt vmcnt(8)
	v_lshlrev_b32_e32 v30, 16, v68
	v_and_b32_e32 v31, 0xffff0000, v68
	v_lshlrev_b32_e32 v32, 16, v69
	v_and_b32_e32 v33, 0xffff0000, v69
	v_lshlrev_b32_e32 v56, 16, v70
	v_and_b32_e32 v57, 0xffff0000, v70
	v_lshlrev_b32_e32 v58, 16, v71
	v_and_b32_e32 v59, 0xffff0000, v71
	v_cndmask_b32_e64 v60, 1.0, 0, s[28:29]
	v_pk_fma_f32 v[8:9], v[60:61], v[32:33], v[8:9] op_sel_hi:[0,1,1]
	v_pk_fma_f32 v[26:27], v[60:61], v[30:31], v[26:27] op_sel_hi:[0,1,1]
	v_pk_fma_f32 v[10:11], v[60:61], v[58:59], v[10:11] op_sel_hi:[0,1,1]
	v_pk_fma_f32 v[28:29], v[60:61], v[56:57], v[28:29] op_sel_hi:[0,1,1]
	s_waitcnt vmcnt(7)
	v_lshlrev_b32_e32 v30, 16, v72
	v_and_b32_e32 v31, 0xffff0000, v72
	v_lshlrev_b32_e32 v32, 16, v73
	v_and_b32_e32 v33, 0xffff0000, v73
	v_lshlrev_b32_e32 v56, 16, v74
	v_and_b32_e32 v57, 0xffff0000, v74
	v_lshlrev_b32_e32 v58, 16, v75
	v_and_b32_e32 v59, 0xffff0000, v75
	v_cndmask_b32_e64 v60, 1.0, 0, s[26:27]
	v_pk_fma_f32 v[26:27], v[60:61], v[30:31], v[26:27] op_sel_hi:[0,1,1]
	v_pk_fma_f32 v[8:9], v[60:61], v[32:33], v[8:9] op_sel_hi:[0,1,1]
	v_pk_fma_f32 v[28:29], v[60:61], v[56:57], v[28:29] op_sel_hi:[0,1,1]
	v_pk_fma_f32 v[10:11], v[60:61], v[58:59], v[10:11] op_sel_hi:[0,1,1]
	s_waitcnt vmcnt(6)
	v_lshlrev_b32_e32 v30, 16, v76
	v_and_b32_e32 v31, 0xffff0000, v76
	v_lshlrev_b32_e32 v32, 16, v77
	v_and_b32_e32 v33, 0xffff0000, v77
	v_lshlrev_b32_e32 v56, 16, v78
	v_and_b32_e32 v57, 0xffff0000, v78
	v_lshlrev_b32_e32 v58, 16, v79
	v_and_b32_e32 v59, 0xffff0000, v79
	v_cndmask_b32_e64 v60, 1.0, 0, s[24:25]
	v_pk_fma_f32 v[8:9], v[60:61], v[32:33], v[8:9] op_sel_hi:[0,1,1]
	v_pk_fma_f32 v[26:27], v[60:61], v[30:31], v[26:27] op_sel_hi:[0,1,1]
	v_pk_fma_f32 v[10:11], v[60:61], v[58:59], v[10:11] op_sel_hi:[0,1,1]
	v_pk_fma_f32 v[28:29], v[60:61], v[56:57], v[28:29] op_sel_hi:[0,1,1]
	s_waitcnt vmcnt(5)
	v_lshlrev_b32_e32 v30, 16, v80
	v_and_b32_e32 v31, 0xffff0000, v80
	v_lshlrev_b32_e32 v32, 16, v81
	v_and_b32_e32 v33, 0xffff0000, v81
	v_lshlrev_b32_e32 v56, 16, v82
	v_and_b32_e32 v57, 0xffff0000, v82
	v_lshlrev_b32_e32 v58, 16, v83
	v_and_b32_e32 v59, 0xffff0000, v83
	v_cndmask_b32_e64 v60, 1.0, 0, s[22:23]
	v_pk_fma_f32 v[26:27], v[60:61], v[30:31], v[26:27] op_sel_hi:[0,1,1]
	v_pk_fma_f32 v[8:9], v[60:61], v[32:33], v[8:9] op_sel_hi:[0,1,1]
	v_pk_fma_f32 v[28:29], v[60:61], v[56:57], v[28:29] op_sel_hi:[0,1,1]
	v_pk_fma_f32 v[10:11], v[60:61], v[58:59], v[10:11] op_sel_hi:[0,1,1]
	s_waitcnt vmcnt(4)
	v_lshlrev_b32_e32 v30, 16, v84
	v_and_b32_e32 v31, 0xffff0000, v84
	v_lshlrev_b32_e32 v32, 16, v85
	v_and_b32_e32 v33, 0xffff0000, v85
	v_lshlrev_b32_e32 v56, 16, v86
	v_and_b32_e32 v57, 0xffff0000, v86
	v_lshlrev_b32_e32 v58, 16, v87
	v_and_b32_e32 v59, 0xffff0000, v87
	v_cndmask_b32_e64 v60, 1.0, 0, s[20:21]
	v_pk_fma_f32 v[8:9], v[60:61], v[32:33], v[8:9] op_sel_hi:[0,1,1]
	v_pk_fma_f32 v[26:27], v[60:61], v[30:31], v[26:27] op_sel_hi:[0,1,1]
	v_pk_fma_f32 v[10:11], v[60:61], v[58:59], v[10:11] op_sel_hi:[0,1,1]
	v_pk_fma_f32 v[28:29], v[60:61], v[56:57], v[28:29] op_sel_hi:[0,1,1]
	s_waitcnt vmcnt(3)
	v_lshlrev_b32_e32 v30, 16, v88
	v_and_b32_e32 v31, 0xffff0000, v88
	v_lshlrev_b32_e32 v32, 16, v89
	v_and_b32_e32 v33, 0xffff0000, v89
	v_lshlrev_b32_e32 v56, 16, v90
	v_and_b32_e32 v57, 0xffff0000, v90
	v_lshlrev_b32_e32 v58, 16, v91
	v_and_b32_e32 v59, 0xffff0000, v91
	v_cndmask_b32_e64 v60, 1.0, 0, s[18:19]
	v_pk_fma_f32 v[26:27], v[60:61], v[30:31], v[26:27] op_sel_hi:[0,1,1]
	v_pk_fma_f32 v[8:9], v[60:61], v[32:33], v[8:9] op_sel_hi:[0,1,1]
	v_pk_fma_f32 v[28:29], v[60:61], v[56:57], v[28:29] op_sel_hi:[0,1,1]
	v_pk_fma_f32 v[10:11], v[60:61], v[58:59], v[10:11] op_sel_hi:[0,1,1]
	s_waitcnt vmcnt(2)
	v_lshlrev_b32_e32 v30, 16, v92
	v_and_b32_e32 v31, 0xffff0000, v92
	v_lshlrev_b32_e32 v32, 16, v93
	v_and_b32_e32 v33, 0xffff0000, v93
	v_lshlrev_b32_e32 v56, 16, v94
	v_and_b32_e32 v57, 0xffff0000, v94
	v_lshlrev_b32_e32 v58, 16, v95
	v_and_b32_e32 v59, 0xffff0000, v95
	v_cndmask_b32_e64 v60, 1.0, 0, s[16:17]
	v_pk_fma_f32 v[8:9], v[60:61], v[32:33], v[8:9] op_sel_hi:[0,1,1]
	v_pk_fma_f32 v[26:27], v[60:61], v[30:31], v[26:27] op_sel_hi:[0,1,1]
	v_pk_fma_f32 v[10:11], v[60:61], v[58:59], v[10:11] op_sel_hi:[0,1,1]
	v_pk_fma_f32 v[28:29], v[60:61], v[56:57], v[28:29] op_sel_hi:[0,1,1]
	s_waitcnt vmcnt(1)
	v_lshlrev_b32_e32 v30, 16, v4
	v_and_b32_e32 v31, 0xffff0000, v4
	v_lshlrev_b32_e32 v4, 16, v5
	v_and_b32_e32 v5, 0xffff0000, v5
	v_lshlrev_b32_e32 v32, 16, v6
	v_and_b32_e32 v33, 0xffff0000, v6
	v_lshlrev_b32_e32 v6, 16, v7
	v_and_b32_e32 v7, 0xffff0000, v7
	v_cndmask_b32_e64 v56, 1.0, 0, s[14:15]
	v_pk_fma_f32 v[26:27], v[56:57], v[30:31], v[26:27] op_sel_hi:[0,1,1]
	v_pk_fma_f32 v[4:5], v[56:57], v[4:5], v[8:9] op_sel_hi:[0,1,1]
	v_pk_fma_f32 v[8:9], v[56:57], v[32:33], v[28:29] op_sel_hi:[0,1,1]
	v_pk_fma_f32 v[6:7], v[56:57], v[6:7], v[10:11] op_sel_hi:[0,1,1]
	s_waitcnt vmcnt(0)
	v_lshlrev_b32_e32 v10, 16, v0
	v_and_b32_e32 v11, 0xffff0000, v0
	v_lshlrev_b32_e32 v0, 16, v1
	v_and_b32_e32 v1, 0xffff0000, v1
	v_lshlrev_b32_e32 v28, 16, v2
	v_and_b32_e32 v29, 0xffff0000, v2
	v_lshlrev_b32_e32 v30, 16, v3
	v_and_b32_e32 v31, 0xffff0000, v3
	v_cndmask_b32_e64 v32, 1.0, 0, s[12:13]
	v_pk_fma_f32 v[2:3], v[32:33], v[0:1], v[4:5] op_sel_hi:[0,1,1]
	v_pk_fma_f32 v[0:1], v[32:33], v[10:11], v[26:27] op_sel_hi:[0,1,1]
	v_pk_fma_f32 v[6:7], v[32:33], v[30:31], v[6:7] op_sel_hi:[0,1,1]
	v_pk_fma_f32 v[4:5], v[32:33], v[28:29], v[8:9] op_sel_hi:[0,1,1]

.LBB0_1374:
	v_ashrrev_i32_e32 v19, 6, v51
	s_waitcnt vmcnt(2)
	v_lshrrev_b32_e32 v0, 4, v51
	v_bfi_b32 v18, -4, v19, v0
	v_lshlrev_b32_e32 v0, 3, v51
	v_cmp_gt_i32_e32 vcc, s7, v18
	v_bfe_u32 v53, v51, 6, 2
	v_lshrrev_b32_e32 v255, 17, v51
	v_add_u32_e32 v53, v53, v255
	v_and_b32_e32 v53, 3, v53
	s_waitcnt vmcnt(1)
	v_and_b32_e32 v4, -4, v19
	v_and_b32_e32 v0, 0x78, v0
	v_bfe_u32 v5, v51, 4, 2
	v_cndmask_b32_e32 v6, 7, v13, vcc
	v_lshl_or_b32 v52, v53, 7, v0
	v_bitop3_b32 v54, v6, v4, v5 bitop3:0xe0
	v_mad_i64_i32 v[0:1], s[10:11], v18, s8, v[14:15]
	v_lshlrev_b32_e32 v16, 1, v52
	v_cmp_eq_u32_e64 s[12:13], 0, v54
	v_lshl_add_u64 v[28:29], v[0:1], 0, v[16:17]
	global_load_dwordx4 v[0:3], v[28:29], off offset:3584
	v_cndmask_b32_e64 v5, -1, 0, s[12:13]
	v_cndmask_b32_e64 v4, v36, 0, s[12:13]
	v_lshl_add_u64 v[4:5], v[28:29], 0, v[4:5]
	global_load_dwordx4 v[8:11], v[4:5], off offset:3584
	v_cmp_lt_i32_e64 s[10:11], s6, v18
	v_cmp_lt_i32_e64 s[14:15], 1, v53
	s_waitcnt vmcnt(1)
	v_lshlrev_b32_e32 v22, 16, v0
	v_and_b32_e32 v23, 0xffff0000, v0
	v_lshlrev_b32_e32 v26, 16, v1
	v_and_b32_e32 v27, 0xffff0000, v1
	v_lshlrev_b32_e32 v20, 16, v2
	v_and_b32_e32 v21, 0xffff0000, v2
	v_lshlrev_b32_e32 v24, 16, v3
	v_and_b32_e32 v25, 0xffff0000, v3
	s_and_saveexec_b64 s[16:17], s[14:15]
	s_xor_b64 s[68:69], exec, s[16:17]
	s_cbranch_execz .LBB0_1380
	v_cmp_lt_i32_e64 s[14:15], 2, v53
	s_and_saveexec_b64 s[16:17], s[14:15]
	s_xor_b64 s[70:71], exec, s[16:17]
	s_cbranch_execz .LBB0_1377
	v_cmp_gt_u32_e64 s[42:43], 2, v54
	v_cmp_gt_u32_e64 s[38:39], 4, v54
	v_cmp_gt_u32_e64 s[40:41], 3, v54
	v_cndmask_b32_e64 v1, -1, 0, s[42:43]
	v_cndmask_b32_e64 v0, v37, 0, s[42:43]
	v_cndmask_b32_e64 v3, -1, 0, s[38:39]
	v_cndmask_b32_e64 v2, v39, 0, s[38:39]
	v_lshl_add_u64 v[0:1], v[28:29], 0, v[0:1]
	v_lshl_add_u64 v[2:3], v[28:29], 0, v[2:3]
	global_load_dwordx4 v[30:33], v[0:1], off offset:3584
	global_load_dwordx4 v[60:63], v[2:3], off offset:3584
	v_cndmask_b32_e64 v1, -1, 0, s[40:41]
	v_cndmask_b32_e64 v0, v38, 0, s[40:41]
	v_cmp_gt_u32_e64 s[36:37], 5, v54
	v_lshl_add_u64 v[0:1], v[28:29], 0, v[0:1]
	v_cmp_gt_u32_e64 s[34:35], 6, v54
	v_cndmask_b32_e64 v5, -1, 0, s[36:37]
	global_load_dwordx4 v[56:59], v[0:1], off offset:3584
	v_cndmask_b32_e64 v4, v40, 0, s[36:37]
	v_cndmask_b32_e64 v7, -1, 0, s[34:35]
	v_cmp_gt_u32_e64 s[30:31], 7, v54
	v_lshl_add_u64 v[4:5], v[28:29], 0, v[4:5]
	v_cndmask_b32_e64 v6, v41, 0, s[34:35]
	v_cmp_gt_u32_e64 s[26:27], 9, v54
	global_load_dwordx4 v[64:67], v[4:5], off offset:3584
	v_cndmask_b32_e64 v1, -1, 0, s[30:31]
	v_cndmask_b32_e64 v0, v42, 0, s[30:31]
	v_lshl_add_u64 v[6:7], v[28:29], 0, v[6:7]
	v_cndmask_b32_e64 v69, -1, 0, s[26:27]
	s_waitcnt vmcnt(4)
	v_lshlrev_b32_e32 v70, 16, v8
	v_and_b32_e32 v71, 0xffff0000, v8
	v_lshlrev_b32_e32 v82, 16, v9
	v_and_b32_e32 v83, 0xffff0000, v9
	v_lshlrev_b32_e32 v4, 16, v10
	v_and_b32_e32 v5, 0xffff0000, v10
	v_lshlrev_b32_e32 v84, 16, v11
	v_and_b32_e32 v85, 0xffff0000, v11
	v_cndmask_b32_e64 v86, 1.0, 0, s[12:13]
	v_cndmask_b32_e64 v68, v44, 0, s[26:27]
	global_load_dwordx4 v[8:11], v[6:7], off offset:3584
	v_lshl_add_u64 v[0:1], v[28:29], 0, v[0:1]
	v_pk_fma_f32 v[98:99], v[86:87], v[70:71], v[22:23] op_sel_hi:[0,1,1]
	v_lshl_add_u64 v[6:7], v[28:29], 0, v[68:69]
	global_load_dwordx4 v[68:71], v[0:1], off offset:3584
	v_cmp_gt_u32_e64 s[28:29], 8, v54
	v_cmp_gt_u32_e64 s[24:25], 10, v54
	v_cmp_gt_u32_e64 s[20:21], 12, v54
	v_cmp_gt_u32_e64 s[18:19], 13, v54
	v_cndmask_b32_e64 v35, -1, 0, s[28:29]
	v_cndmask_b32_e64 v73, -1, 0, s[24:25]
	v_cmp_gt_u32_e64 s[22:23], 11, v54
	v_cndmask_b32_e64 v3, -1, 0, s[20:21]
	v_cndmask_b32_e64 v77, -1, 0, s[18:19]
	v_cmp_gt_u32_e64 s[16:17], 14, v54
	v_cmp_gt_u32_e64 s[14:15], 15, v54
	v_cndmask_b32_e64 v34, v43, 0, s[28:29]
	v_cndmask_b32_e64 v72, v45, 0, s[24:25]
	v_cndmask_b32_e64 v2, v47, 0, s[20:21]
	v_cndmask_b32_e64 v76, v48, 0, s[18:19]
	v_cndmask_b32_e64 v75, -1, 0, s[22:23]
	v_cndmask_b32_e64 v79, -1, 0, s[16:17]
	v_cndmask_b32_e64 v81, -1, 0, s[14:15]
	v_cndmask_b32_e64 v74, v46, 0, s[22:23]
	v_cndmask_b32_e64 v78, v49, 0, s[16:17]
	v_cndmask_b32_e64 v80, v50, 0, s[14:15]
	v_pk_fma_f32 v[102:103], v[86:87], v[4:5], v[20:21] op_sel_hi:[0,1,1]
	v_lshl_add_u64 v[4:5], v[28:29], 0, v[34:35]
	v_lshl_add_u64 v[0:1], v[28:29], 0, v[72:73]
	v_lshl_add_u64 v[2:3], v[28:29], 0, v[2:3]
	v_lshl_add_u64 v[92:93], v[28:29], 0, v[76:77]
	v_pk_fma_f32 v[96:97], v[86:87], v[82:83], v[26:27] op_sel_hi:[0,1,1]
	v_pk_fma_f32 v[100:101], v[86:87], v[84:85], v[24:25] op_sel_hi:[0,1,1]
	v_lshl_add_u64 v[34:35], v[28:29], 0, v[74:75]
	v_lshl_add_u64 v[104:105], v[28:29], 0, v[78:79]
	v_lshl_add_u64 v[28:29], v[28:29], 0, v[80:81]
	global_load_dwordx4 v[72:75], v[4:5], off offset:3584
	global_load_dwordx4 v[76:79], v[6:7], off offset:3584
	global_load_dwordx4 v[80:83], v[0:1], off offset:3584
	global_load_dwordx4 v[84:87], v[34:35], off offset:3584
	global_load_dwordx4 v[88:91], v[2:3], off offset:3584
	s_nop 0
	global_load_dwordx4 v[92:95], v[92:93], off offset:3584
	s_nop 0
	global_load_dwordx4 v[4:7], v[104:105], off offset:3584
	global_load_dwordx4 v[0:3], v[28:29], off offset:3584
	v_cndmask_b32_e64 v104, 1.0, 0, s[42:43]
	s_waitcnt vmcnt(13)
	v_lshlrev_b32_e32 v28, 16, v30
	v_and_b32_e32 v29, 0xffff0000, v30
	v_lshlrev_b32_e32 v30, 16, v31
	v_and_b32_e32 v31, 0xffff0000, v31
	v_lshlrev_b32_e32 v34, 16, v32
	v_and_b32_e32 v35, 0xffff0000, v32
	v_lshlrev_b32_e32 v32, 16, v33
	v_and_b32_e32 v33, 0xffff0000, v33
	v_pk_fma_f32 v[28:29], v[104:105], v[28:29], v[98:99] op_sel_hi:[0,1,1]
	v_pk_fma_f32 v[30:31], v[104:105], v[30:31], v[96:97] op_sel_hi:[0,1,1]
	v_pk_fma_f32 v[34:35], v[104:105], v[34:35], v[102:103] op_sel_hi:[0,1,1]
	v_pk_fma_f32 v[32:33], v[104:105], v[32:33], v[100:101] op_sel_hi:[0,1,1]
	s_waitcnt vmcnt(11)
	v_lshlrev_b32_e32 v96, 16, v56
	v_and_b32_e32 v97, 0xffff0000, v56
	v_lshlrev_b32_e32 v56, 16, v57
	v_and_b32_e32 v57, 0xffff0000, v57
	v_lshlrev_b32_e32 v98, 16, v58
	v_and_b32_e32 v99, 0xffff0000, v58
	v_lshlrev_b32_e32 v58, 16, v59
	v_and_b32_e32 v59, 0xffff0000, v59
	v_cndmask_b32_e64 v100, 1.0, 0, s[40:41]
	v_pk_fma_f32 v[30:31], v[100:101], v[56:57], v[30:31] op_sel_hi:[0,1,1]
	v_pk_fma_f32 v[28:29], v[100:101], v[96:97], v[28:29] op_sel_hi:[0,1,1]
	v_pk_fma_f32 v[32:33], v[100:101], v[58:59], v[32:33] op_sel_hi:[0,1,1]
	v_pk_fma_f32 v[34:35], v[100:101], v[98:99], v[34:35] op_sel_hi:[0,1,1]
	v_lshlrev_b32_e32 v56, 16, v60
	v_and_b32_e32 v57, 0xffff0000, v60
	v_lshlrev_b32_e32 v58, 16, v61
	v_and_b32_e32 v59, 0xffff0000, v61
	v_lshlrev_b32_e32 v60, 16, v62
	v_and_b32_e32 v61, 0xffff0000, v62
	v_lshlrev_b32_e32 v62, 16, v63
	v_and_b32_e32 v63, 0xffff0000, v63
	v_cndmask_b32_e64 v96, 1.0, 0, s[38:39]
	v_pk_fma_f32 v[28:29], v[96:97], v[56:57], v[28:29] op_sel_hi:[0,1,1]
	v_pk_fma_f32 v[30:31], v[96:97], v[58:59], v[30:31] op_sel_hi:[0,1,1]
	v_pk_fma_f32 v[34:35], v[96:97], v[60:61], v[34:35] op_sel_hi:[0,1,1]
	v_pk_fma_f32 v[32:33], v[96:97], v[62:63], v[32:33] op_sel_hi:[0,1,1]
	s_waitcnt vmcnt(10)
	v_lshlrev_b32_e32 v56, 16, v64
	v_and_b32_e32 v57, 0xffff0000, v64
	v_lshlrev_b32_e32 v58, 16, v65
	v_and_b32_e32 v59, 0xffff0000, v65
	v_lshlrev_b32_e32 v60, 16, v66
	v_and_b32_e32 v61, 0xffff0000, v66
	v_lshlrev_b32_e32 v62, 16, v67
	v_and_b32_e32 v63, 0xffff0000, v67
	v_cndmask_b32_e64 v64, 1.0, 0, s[36:37]
	v_pk_fma_f32 v[30:31], v[64:65], v[58:59], v[30:31] op_sel_hi:[0,1,1]
	v_pk_fma_f32 v[28:29], v[64:65], v[56:57], v[28:29] op_sel_hi:[0,1,1]
	v_pk_fma_f32 v[32:33], v[64:65], v[62:63], v[32:33] op_sel_hi:[0,1,1]
	v_pk_fma_f32 v[34:35], v[64:65], v[60:61], v[34:35] op_sel_hi:[0,1,1]
	s_waitcnt vmcnt(9)
	v_lshlrev_b32_e32 v56, 16, v8
	v_and_b32_e32 v57, 0xffff0000, v8
	v_lshlrev_b32_e32 v8, 16, v9
	v_and_b32_e32 v9, 0xffff0000, v9
	v_lshlrev_b32_e32 v58, 16, v10
	v_and_b32_e32 v59, 0xffff0000, v10
	v_lshlrev_b32_e32 v10, 16, v11
	v_and_b32_e32 v11, 0xffff0000, v11
	v_cndmask_b32_e64 v60, 1.0, 0, s[34:35]
	v_pk_fma_f32 v[28:29], v[60:61], v[56:57], v[28:29] op_sel_hi:[0,1,1]
	v_pk_fma_f32 v[8:9], v[60:61], v[8:9], v[30:31] op_sel_hi:[0,1,1]
	v_pk_fma_f32 v[30:31], v[60:61], v[58:59], v[34:35] op_sel_hi:[0,1,1]
	v_pk_fma_f32 v[10:11], v[60:61], v[10:11], v[32:33] op_sel_hi:[0,1,1]
	s_waitcnt vmcnt(8)
	v_lshlrev_b32_e32 v32, 16, v68
	v_and_b32_e32 v33, 0xffff0000, v68
	v_lshlrev_b32_e32 v34, 16, v69
	v_and_b32_e32 v35, 0xffff0000, v69
	v_lshlrev_b32_e32 v56, 16, v70
	v_and_b32_e32 v57, 0xffff0000, v70
	v_lshlrev_b32_e32 v58, 16, v71
	v_and_b32_e32 v59, 0xffff0000, v71
	v_cndmask_b32_e64 v60, 1.0, 0, s[30:31]
	v_pk_fma_f32 v[8:9], v[60:61], v[34:35], v[8:9] op_sel_hi:[0,1,1]
	v_pk_fma_f32 v[28:29], v[60:61], v[32:33], v[28:29] op_sel_hi:[0,1,1]
	v_pk_fma_f32 v[10:11], v[60:61], v[58:59], v[10:11] op_sel_hi:[0,1,1]
	v_pk_fma_f32 v[30:31], v[60:61], v[56:57], v[30:31] op_sel_hi:[0,1,1]
	s_waitcnt vmcnt(7)
	v_lshlrev_b32_e32 v32, 16, v72
	v_and_b32_e32 v33, 0xffff0000, v72
	v_lshlrev_b32_e32 v34, 16, v73
	v_and_b32_e32 v35, 0xffff0000, v73
	v_lshlrev_b32_e32 v56, 16, v74
	v_and_b32_e32 v57, 0xffff0000, v74
	v_lshlrev_b32_e32 v58, 16, v75
	v_and_b32_e32 v59, 0xffff0000, v75
	v_cndmask_b32_e64 v60, 1.0, 0, s[28:29]
	v_pk_fma_f32 v[28:29], v[60:61], v[32:33], v[28:29] op_sel_hi:[0,1,1]
	v_pk_fma_f32 v[8:9], v[60:61], v[34:35], v[8:9] op_sel_hi:[0,1,1]
	v_pk_fma_f32 v[30:31], v[60:61], v[56:57], v[30:31] op_sel_hi:[0,1,1]
	v_pk_fma_f32 v[10:11], v[60:61], v[58:59], v[10:11] op_sel_hi:[0,1,1]
	s_waitcnt vmcnt(6)
	v_lshlrev_b32_e32 v32, 16, v76
	v_and_b32_e32 v33, 0xffff0000, v76
	v_lshlrev_b32_e32 v34, 16, v77
	v_and_b32_e32 v35, 0xffff0000, v77
	v_lshlrev_b32_e32 v56, 16, v78
	v_and_b32_e32 v57, 0xffff0000, v78
	v_lshlrev_b32_e32 v58, 16, v79
	v_and_b32_e32 v59, 0xffff0000, v79
	v_cndmask_b32_e64 v60, 1.0, 0, s[26:27]
	v_pk_fma_f32 v[8:9], v[60:61], v[34:35], v[8:9] op_sel_hi:[0,1,1]
	v_pk_fma_f32 v[28:29], v[60:61], v[32:33], v[28:29] op_sel_hi:[0,1,1]
	v_pk_fma_f32 v[10:11], v[60:61], v[58:59], v[10:11] op_sel_hi:[0,1,1]
	v_pk_fma_f32 v[30:31], v[60:61], v[56:57], v[30:31] op_sel_hi:[0,1,1]
	s_waitcnt vmcnt(5)
	v_lshlrev_b32_e32 v32, 16, v80
	v_and_b32_e32 v33, 0xffff0000, v80
	v_lshlrev_b32_e32 v34, 16, v81
	v_and_b32_e32 v35, 0xffff0000, v81
	v_lshlrev_b32_e32 v56, 16, v82
	v_and_b32_e32 v57, 0xffff0000, v82
	v_lshlrev_b32_e32 v58, 16, v83
	v_and_b32_e32 v59, 0xffff0000, v83
	v_cndmask_b32_e64 v60, 1.0, 0, s[24:25]
	v_pk_fma_f32 v[28:29], v[60:61], v[32:33], v[28:29] op_sel_hi:[0,1,1]
	v_pk_fma_f32 v[8:9], v[60:61], v[34:35], v[8:9] op_sel_hi:[0,1,1]
	v_pk_fma_f32 v[30:31], v[60:61], v[56:57], v[30:31] op_sel_hi:[0,1,1]
	v_pk_fma_f32 v[10:11], v[60:61], v[58:59], v[10:11] op_sel_hi:[0,1,1]
	s_waitcnt vmcnt(4)
	v_lshlrev_b32_e32 v32, 16, v84
	v_and_b32_e32 v33, 0xffff0000, v84
	v_lshlrev_b32_e32 v34, 16, v85
	v_and_b32_e32 v35, 0xffff0000, v85
	v_lshlrev_b32_e32 v56, 16, v86
	v_and_b32_e32 v57, 0xffff0000, v86
	v_lshlrev_b32_e32 v58, 16, v87
	v_and_b32_e32 v59, 0xffff0000, v87
	v_cndmask_b32_e64 v60, 1.0, 0, s[22:23]
	v_pk_fma_f32 v[8:9], v[60:61], v[34:35], v[8:9] op_sel_hi:[0,1,1]
	v_pk_fma_f32 v[28:29], v[60:61], v[32:33], v[28:29] op_sel_hi:[0,1,1]
	v_pk_fma_f32 v[10:11], v[60:61], v[58:59], v[10:11] op_sel_hi:[0,1,1]
	v_pk_fma_f32 v[30:31], v[60:61], v[56:57], v[30:31] op_sel_hi:[0,1,1]
	s_waitcnt vmcnt(3)
	v_lshlrev_b32_e32 v32, 16, v88
	v_and_b32_e32 v33, 0xffff0000, v88
	v_lshlrev_b32_e32 v34, 16, v89
	v_and_b32_e32 v35, 0xffff0000, v89
	v_lshlrev_b32_e32 v56, 16, v90
	v_and_b32_e32 v57, 0xffff0000, v90
	v_lshlrev_b32_e32 v58, 16, v91
	v_and_b32_e32 v59, 0xffff0000, v91
	v_cndmask_b32_e64 v60, 1.0, 0, s[20:21]
	v_pk_fma_f32 v[28:29], v[60:61], v[32:33], v[28:29] op_sel_hi:[0,1,1]
	v_pk_fma_f32 v[8:9], v[60:61], v[34:35], v[8:9] op_sel_hi:[0,1,1]
	v_pk_fma_f32 v[30:31], v[60:61], v[56:57], v[30:31] op_sel_hi:[0,1,1]
	v_pk_fma_f32 v[10:11], v[60:61], v[58:59], v[10:11] op_sel_hi:[0,1,1]
	s_waitcnt vmcnt(2)
	v_lshlrev_b32_e32 v32, 16, v92
	v_and_b32_e32 v33, 0xffff0000, v92
	v_lshlrev_b32_e32 v34, 16, v93
	v_and_b32_e32 v35, 0xffff0000, v93
	v_lshlrev_b32_e32 v56, 16, v94
	v_and_b32_e32 v57, 0xffff0000, v94
	v_lshlrev_b32_e32 v58, 16, v95
	v_and_b32_e32 v59, 0xffff0000, v95
	v_cndmask_b32_e64 v60, 1.0, 0, s[18:19]
	v_pk_fma_f32 v[8:9], v[60:61], v[34:35], v[8:9] op_sel_hi:[0,1,1]
	v_pk_fma_f32 v[28:29], v[60:61], v[32:33], v[28:29] op_sel_hi:[0,1,1]
	v_pk_fma_f32 v[10:11], v[60:61], v[58:59], v[10:11] op_sel_hi:[0,1,1]
	v_pk_fma_f32 v[30:31], v[60:61], v[56:57], v[30:31] op_sel_hi:[0,1,1]
	s_waitcnt vmcnt(1)
	v_lshlrev_b32_e32 v32, 16, v4
	v_and_b32_e32 v33, 0xffff0000, v4
	v_lshlrev_b32_e32 v4, 16, v5
	v_and_b32_e32 v5, 0xffff0000, v5
	v_lshlrev_b32_e32 v34, 16, v6
	v_and_b32_e32 v35, 0xffff0000, v6
	v_lshlrev_b32_e32 v6, 16, v7
	v_and_b32_e32 v7, 0xffff0000, v7
	v_cndmask_b32_e64 v56, 1.0, 0, s[16:17]
	v_pk_fma_f32 v[28:29], v[56:57], v[32:33], v[28:29] op_sel_hi:[0,1,1]
	v_pk_fma_f32 v[4:5], v[56:57], v[4:5], v[8:9] op_sel_hi:[0,1,1]
	v_pk_fma_f32 v[8:9], v[56:57], v[34:35], v[30:31] op_sel_hi:[0,1,1]
	v_pk_fma_f32 v[6:7], v[56:57], v[6:7], v[10:11] op_sel_hi:[0,1,1]
	s_waitcnt vmcnt(0)
	v_lshlrev_b32_e32 v10, 16, v0
	v_and_b32_e32 v11, 0xffff0000, v0
	v_lshlrev_b32_e32 v0, 16, v1
	v_and_b32_e32 v1, 0xffff0000, v1
	v_lshlrev_b32_e32 v30, 16, v2
	v_and_b32_e32 v31, 0xffff0000, v2
	v_lshlrev_b32_e32 v32, 16, v3
	v_and_b32_e32 v33, 0xffff0000, v3
	v_cndmask_b32_e64 v34, 1.0, 0, s[14:15]
	v_pk_fma_f32 v[2:3], v[34:35], v[0:1], v[4:5] op_sel_hi:[0,1,1]
	v_pk_fma_f32 v[0:1], v[34:35], v[10:11], v[28:29] op_sel_hi:[0,1,1]
	v_pk_fma_f32 v[6:7], v[34:35], v[32:33], v[6:7] op_sel_hi:[0,1,1]
	v_pk_fma_f32 v[4:5], v[34:35], v[30:31], v[8:9] op_sel_hi:[0,1,1]
